# attnA: leading K-fragment LDS reads of each step's QK block issued right after the barrier, ahead of the DMA issue code
# baseline (speedup 1.0000x reference)
.LBB0_1367:
	v_readfirstlane_b32 s38, v202
	ds_read_b128 v[2:5], v222 offset:24576
	ds_read_b128 v[6:9], v222 offset:28672
	ds_read_b128 v[10:13], v223 offset:24576
	ds_read_b128 v[244:247], v223 offset:28672
	s_add_i32 s16, s34, 2
	s_cmp_lt_u32 s34, s29
	s_cselect_b64 s[20:21], -1, 0
	s_cmp_ge_u32 s34, s29
	s_cselect_b64 s[18:19], -1, 0
	s_and_b64 vcc, exec, s[18:19]
	s_cbranch_vccnz .LBB0_1369
	s_mov_b32 s17, s83
	s_lshl_b64 s[4:5], s[16:17], 18
	s_add_u32 s4, s6, s4
	s_addc_u32 s5, s7, s5
	s_add_u32 s4, s4, s84
	s_addc_u32 s5, s5, s85
	s_mov_b32 m0, s38
	s_nop 0
	global_load_lds_dwordx4 v196, s[4:5]
	s_add_u32 m0, s38, 0x1000
	s_nop 0
	global_load_lds_dwordx4 v197, s[4:5]
.LBB0_1369:
	s_or_b32 s82, s34, 1
	s_lshl_b64 s[4:5], s[82:83], 7
	s_add_u32 s4, s8, s4
	s_addc_u32 s5, s9, s5
	s_add_u32 m0, s38, 0x8000
	s_nop 0
	global_load_lds_dwordx4 v198, s[4:5]
	s_add_u32 m0, s38, 0x9000
	s_nop 0
	global_load_lds_dwordx4 v199, s[4:5]
	s_add_u32 m0, s38, 0xa000
	s_nop 0
	global_load_lds_dwordx4 v200, s[4:5]
	s_add_u32 m0, s38, 0xb000
	s_nop 0
	global_load_lds_dwordx4 v201, s[4:5]
	v_cmp_lt_i32_e64 s[4:5], s34, v226
	s_and_saveexec_b64 s[22:23], s[4:5]
	s_cbranch_execz .LBB0_1371
	s_waitcnt lgkmcnt(3)
	v_mfma_f32_32x32x16_bf16 v[128:143], v[2:5], v[160:163], v[16:31]
	v_exp_f32_e32 v32, v32
	v_exp_f32_e32 v33, v33
	ds_read_b128 v[2:5], v224 offset:24576
	s_waitcnt lgkmcnt(3)
	v_mfma_f32_32x32x16_bf16 v[144:159], v[6:9], v[160:163], v[16:31]
	v_exp_f32_e32 v34, v34
	v_exp_f32_e32 v35, v35
	ds_read_b128 v[6:9], v224 offset:28672
	s_waitcnt lgkmcnt(3)
	v_mfma_f32_32x32x16_bf16 v[128:143], v[10:13], v[164:167], v[128:143]
	v_exp_f32_e32 v36, v36
	v_exp_f32_e32 v37, v37
	v_add_f32_e32 v0, 0, v32
	ds_read_b128 v[10:13], v225 offset:24576
	s_waitcnt lgkmcnt(3)
	v_mfma_f32_32x32x16_bf16 v[144:159], v[244:247], v[164:167], v[144:159]
	v_exp_f32_e32 v38, v38
	v_exp_f32_e32 v39, v39
	v_add_f32_e32 v0, v33, v0
	ds_read_b128 v[244:247], v225 offset:28672
	s_waitcnt lgkmcnt(3)
	v_mfma_f32_32x32x16_bf16 v[128:143], v[2:5], v[168:171], v[128:143]
	v_cvt_pk_bf16_f32 v208, v32, v33
	v_add_f32_e32 v0, v34, v0
	v_add_f32_e32 v0, v35, v0
	s_waitcnt lgkmcnt(2)
	v_mfma_f32_32x32x16_bf16 v[144:159], v[6:9], v[168:171], v[144:159]
	v_cvt_pk_bf16_f32 v209, v34, v35
	v_add_f32_e32 v0, v36, v0
	v_add_f32_e32 v0, v37, v0
	s_waitcnt lgkmcnt(1)
	v_mfma_f32_32x32x16_bf16 v[128:143], v[10:13], v[172:175], v[128:143]
	v_cvt_pk_bf16_f32 v210, v36, v37
	v_add_f32_e32 v0, v38, v0
	s_waitcnt lgkmcnt(0)
	v_mfma_f32_32x32x16_bf16 v[144:159], v[244:247], v[172:175], v[144:159]
	v_cvt_pk_bf16_f32 v211, v38, v39
	v_add_f32_e32 v0, v39, v0
	s_or_b64 exec, exec, s[22:23]
	v_cmp_le_i32_e32 vcc, s34, v226
	s_and_saveexec_b64 s[22:23], vcc
	ds_read_b64 v[6:7], v228 offset:8192
	ds_read_b64 v[8:9], v229 offset:8192
	ds_read_b64 v[10:11], v230 offset:20480
	ds_read_b64 v[12:13], v231 offset:20480
	ds_read_b64 v[244:245], v230 offset:12288
	ds_read_b64 v[246:247], v231 offset:12288
	ds_read_b64 v[32:33], v230 offset:16384
	ds_read_b64 v[34:35], v231 offset:16384
	ds_read_b64 v[36:37], v232 offset:8192
	ds_read_b64 v[38:39], v233 offset:8192
	s_waitcnt lgkmcnt(8)
	v_mfma_f32_32x32x16_bf16 v[112:127], v[6:9], v[208:211], v[112:127]
	ds_read_b64 v[6:7], v234 offset:20480
	ds_read_b64 v[8:9], v235 offset:20480
	v_exp_f32_e32 v40, v40
	v_exp_f32_e32 v41, v41
	s_waitcnt lgkmcnt(8)
	v_mfma_f32_32x32x16_bf16 v[64:79], v[10:13], v[208:211], v[64:79]
	ds_read_b64 v[10:11], v234 offset:12288
	ds_read_b64 v[12:13], v235 offset:12288
	v_exp_f32_e32 v42, v42
	v_exp_f32_e32 v43, v43
	v_add_f32_e32 v0, v40, v0
	v_add_f32_e32 v0, v41, v0
	s_waitcnt lgkmcnt(8)
	v_mfma_f32_32x32x16_bf16 v[96:111], v[244:247], v[208:211], v[96:111]
	ds_read_b64 v[244:245], v234 offset:16384
	ds_read_b64 v[246:247], v235 offset:16384
	v_exp_f32_e32 v44, v44
	v_exp_f32_e32 v45, v45
	v_add_f32_e32 v0, v42, v0
	v_add_f32_e32 v0, v43, v0
	s_waitcnt lgkmcnt(8)
	v_mfma_f32_32x32x16_bf16 v[80:95], v[32:35], v[208:211], v[80:95]
	ds_read_b64 v[32:33], v236 offset:8192
	ds_read_b64 v[34:35], v237 offset:8192
	v_exp_f32_e32 v46, v46
	v_exp_f32_e32 v47, v47
	v_add_f32_e32 v0, v44, v0
	v_add_f32_e32 v0, v45, v0
	v_add_f32_e32 v0, v46, v0
	v_add_f32_e32 v0, v47, v0
	v_cvt_pk_bf16_f32 v2, v40, v41
	v_cvt_pk_bf16_f32 v3, v42, v43
	v_cvt_pk_bf16_f32 v4, v44, v45
	v_cvt_pk_bf16_f32 v5, v46, v47
	s_nop 1
	ds_read_b64 v[40:41], v238 offset:20480
	ds_read_b64 v[42:43], v239 offset:20480
	s_waitcnt lgkmcnt(10)
	v_mfma_f32_32x32x16_bf16 v[112:127], v[36:39], v[2:5], v[112:127]
	ds_read_b64 v[44:45], v238 offset:12288
	ds_read_b64 v[46:47], v239 offset:12288
	v_exp_f32_e32 v48, v48
	v_exp_f32_e32 v49, v49
	s_waitcnt lgkmcnt(10)
	v_mfma_f32_32x32x16_bf16 v[64:79], v[6:9], v[2:5], v[64:79]
	ds_read_b64 v[36:37], v238 offset:16384
	ds_read_b64 v[38:39], v239 offset:16384
	v_exp_f32_e32 v50, v50
	v_exp_f32_e32 v51, v51
	v_add_f32_e32 v0, v48, v0
	v_add_f32_e32 v0, v49, v0
	s_waitcnt lgkmcnt(10)
	v_mfma_f32_32x32x16_bf16 v[96:111], v[10:13], v[2:5], v[96:111]
	ds_read_b64 v[6:7], v240 offset:8192
	ds_read_b64 v[8:9], v241 offset:8192
	v_exp_f32_e32 v52, v52
	v_exp_f32_e32 v53, v53
	v_add_f32_e32 v0, v50, v0
	v_add_f32_e32 v0, v51, v0
	s_waitcnt lgkmcnt(10)
	v_mfma_f32_32x32x16_bf16 v[80:95], v[244:247], v[2:5], v[80:95]
	ds_read_b64 v[10:11], v242 offset:12288
	ds_read_b64 v[12:13], v243 offset:12288
	v_exp_f32_e32 v54, v54
	v_exp_f32_e32 v55, v55
	v_add_f32_e32 v0, v52, v0
	v_add_f32_e32 v0, v53, v0
	v_add_f32_e32 v0, v54, v0
	v_add_f32_e32 v0, v55, v0
	v_cvt_pk_bf16_f32 v2, v48, v49
	v_cvt_pk_bf16_f32 v3, v50, v51
	v_cvt_pk_bf16_f32 v4, v52, v53
	v_cvt_pk_bf16_f32 v5, v54, v55
	s_nop 1
	ds_read_b64 v[244:245], v242 offset:16384
	ds_read_b64 v[246:247], v243 offset:16384
	s_waitcnt lgkmcnt(12)
	v_mfma_f32_32x32x16_bf16 v[112:127], v[32:35], v[2:5], v[112:127]
	ds_read_b64 v[48:49], v242 offset:20480
	ds_read_b64 v[50:51], v243 offset:20480
	v_exp_f32_e32 v56, v56
	v_exp_f32_e32 v57, v57
	s_waitcnt lgkmcnt(12)
	v_mfma_f32_32x32x16_bf16 v[64:79], v[40:43], v[2:5], v[64:79]
	v_exp_f32_e32 v58, v58
	v_exp_f32_e32 v59, v59
	v_add_f32_e32 v0, v56, v0
	v_add_f32_e32 v0, v57, v0
	s_waitcnt lgkmcnt(10)
	v_mfma_f32_32x32x16_bf16 v[96:111], v[44:47], v[2:5], v[96:111]
	v_exp_f32_e32 v60, v60
	v_exp_f32_e32 v61, v61
	v_add_f32_e32 v0, v58, v0
	v_add_f32_e32 v0, v59, v0
	s_waitcnt lgkmcnt(8)
	v_mfma_f32_32x32x16_bf16 v[80:95], v[36:39], v[2:5], v[80:95]
	v_exp_f32_e32 v62, v62
	v_exp_f32_e32 v63, v63
	v_add_f32_e32 v0, v60, v0
	v_add_f32_e32 v0, v61, v0
	v_add_f32_e32 v0, v62, v0
	v_add_f32_e32 v0, v63, v0
	v_cvt_pk_bf16_f32 v2, v56, v57
	v_cvt_pk_bf16_f32 v3, v58, v59
	v_cvt_pk_bf16_f32 v4, v60, v61
	v_cvt_pk_bf16_f32 v5, v62, v63
	s_nop 1
	s_waitcnt lgkmcnt(6)
	v_mfma_f32_32x32x16_bf16 v[112:127], v[6:9], v[2:5], v[112:127]
	s_waitcnt lgkmcnt(4)
	v_mfma_f32_32x32x16_bf16 v[96:111], v[10:13], v[2:5], v[96:111]
	s_waitcnt lgkmcnt(2)
	v_mfma_f32_32x32x16_bf16 v[80:95], v[244:247], v[2:5], v[80:95]
	s_waitcnt lgkmcnt(0)
	v_mfma_f32_32x32x16_bf16 v[64:79], v[48:51], v[2:5], v[64:79]
	v_add_f32_e32 v227, v227, v0
	s_branch .LBB0_1373

.LBB0_1378:
	ds_read_b128 v[2:5], v222
	ds_read_b128 v[6:9], v222 offset:4096
	ds_read_b128 v[10:13], v223
	ds_read_b128 v[244:247], v223 offset:4096
	s_add_i32 s82, s34, 3
	s_cmp_ge_u32 s82, s30
	s_cbranch_scc1 .LBB0_1382
	s_lshl_b64 s[22:23], s[82:83], 18
	s_add_u32 s22, s6, s22
	s_addc_u32 s23, s7, s23
	s_add_u32 s22, s22, s84
	s_addc_u32 s23, s23, s85
	s_add_u32 m0, s38, 0x6000
	s_nop 0
	global_load_lds_dwordx4 v196, s[22:23]
	s_add_u32 m0, s38, 0x7000
	s_nop 0
	global_load_lds_dwordx4 v197, s[22:23]
	s_andn2_b64 vcc, exec, s[20:21]
	s_cbranch_vccz .LBB0_1383

.LBB0_1381:
	s_waitcnt lgkmcnt(3)
	v_mfma_f32_32x32x16_bf16 v[32:47], v[2:5], v[160:163], v[16:31]
	v_exp_f32_e32 v128, v128
	v_exp_f32_e32 v129, v129
	ds_read_b128 v[2:5], v224
	s_waitcnt lgkmcnt(3)
	v_mfma_f32_32x32x16_bf16 v[48:63], v[6:9], v[160:163], v[16:31]
	v_exp_f32_e32 v130, v130
	v_exp_f32_e32 v131, v131
	ds_read_b128 v[6:9], v224 offset:4096
	s_waitcnt lgkmcnt(3)
	v_mfma_f32_32x32x16_bf16 v[32:47], v[10:13], v[164:167], v[32:47]
	v_exp_f32_e32 v132, v132
	v_exp_f32_e32 v133, v133
	v_add_f32_e32 v0, 0, v128
	ds_read_b128 v[10:13], v225
	s_waitcnt lgkmcnt(3)
	v_mfma_f32_32x32x16_bf16 v[48:63], v[244:247], v[164:167], v[48:63]
	v_exp_f32_e32 v134, v134
	v_exp_f32_e32 v135, v135
	v_add_f32_e32 v0, v129, v0
	ds_read_b128 v[244:247], v225 offset:4096
	s_waitcnt lgkmcnt(3)
	v_mfma_f32_32x32x16_bf16 v[32:47], v[2:5], v[168:171], v[32:47]
	v_cvt_pk_bf16_f32 v208, v128, v129
	v_add_f32_e32 v0, v130, v0
	v_add_f32_e32 v0, v131, v0
	s_waitcnt lgkmcnt(2)
	v_mfma_f32_32x32x16_bf16 v[48:63], v[6:9], v[168:171], v[48:63]
	v_cvt_pk_bf16_f32 v209, v130, v131
	v_add_f32_e32 v0, v132, v0
	v_add_f32_e32 v0, v133, v0
	s_waitcnt lgkmcnt(1)
	v_mfma_f32_32x32x16_bf16 v[32:47], v[10:13], v[172:175], v[32:47]
	v_cvt_pk_bf16_f32 v210, v132, v133
	v_add_f32_e32 v0, v134, v0
	s_waitcnt lgkmcnt(0)
	v_mfma_f32_32x32x16_bf16 v[48:63], v[244:247], v[172:175], v[48:63]
	v_cvt_pk_bf16_f32 v211, v134, v135
	v_add_f32_e32 v0, v135, v0
	s_or_b64 exec, exec, s[20:21]
	s_and_saveexec_b64 s[20:21], s[4:5]
	ds_read_b64 v[6:7], v228 offset:32768
	ds_read_b64 v[8:9], v229 offset:32768
	ds_read_b64 v[10:11], v230 offset:45056
	ds_read_b64 v[12:13], v231 offset:45056
	ds_read_b64 v[244:245], v230 offset:36864
	ds_read_b64 v[246:247], v231 offset:36864
	ds_read_b64 v[128:129], v230 offset:40960
	ds_read_b64 v[130:131], v231 offset:40960
	ds_read_b64 v[132:133], v232 offset:32768
	ds_read_b64 v[134:135], v233 offset:32768
	s_waitcnt lgkmcnt(8)
	v_mfma_f32_32x32x16_bf16 v[112:127], v[6:9], v[208:211], v[112:127]
	ds_read_b64 v[6:7], v234 offset:45056
	ds_read_b64 v[8:9], v235 offset:45056
	v_exp_f32_e32 v136, v136
	v_exp_f32_e32 v137, v137
	s_waitcnt lgkmcnt(8)
	v_mfma_f32_32x32x16_bf16 v[64:79], v[10:13], v[208:211], v[64:79]
	ds_read_b64 v[10:11], v234 offset:36864
	ds_read_b64 v[12:13], v235 offset:36864
	v_exp_f32_e32 v138, v138
	v_exp_f32_e32 v139, v139
	v_add_f32_e32 v0, v136, v0
	v_add_f32_e32 v0, v137, v0
	s_waitcnt lgkmcnt(8)
	v_mfma_f32_32x32x16_bf16 v[96:111], v[244:247], v[208:211], v[96:111]
	ds_read_b64 v[244:245], v234 offset:40960
	ds_read_b64 v[246:247], v235 offset:40960
	v_exp_f32_e32 v140, v140
	v_exp_f32_e32 v141, v141
	v_add_f32_e32 v0, v138, v0
	v_add_f32_e32 v0, v139, v0
	s_waitcnt lgkmcnt(8)
	v_mfma_f32_32x32x16_bf16 v[80:95], v[128:131], v[208:211], v[80:95]
	ds_read_b64 v[128:129], v236 offset:32768
	ds_read_b64 v[130:131], v237 offset:32768
	v_exp_f32_e32 v142, v142
	v_exp_f32_e32 v143, v143
	v_add_f32_e32 v0, v140, v0
	v_add_f32_e32 v0, v141, v0
	v_add_f32_e32 v0, v142, v0
	v_add_f32_e32 v0, v143, v0
	v_cvt_pk_bf16_f32 v2, v136, v137
	v_cvt_pk_bf16_f32 v3, v138, v139
	v_cvt_pk_bf16_f32 v4, v140, v141
	v_cvt_pk_bf16_f32 v5, v142, v143
	s_nop 1
	ds_read_b64 v[136:137], v238 offset:45056
	ds_read_b64 v[138:139], v239 offset:45056
	s_waitcnt lgkmcnt(10)
	v_mfma_f32_32x32x16_bf16 v[112:127], v[132:135], v[2:5], v[112:127]
	ds_read_b64 v[140:141], v238 offset:36864
	ds_read_b64 v[142:143], v239 offset:36864
	v_exp_f32_e32 v144, v144
	v_exp_f32_e32 v145, v145
	s_waitcnt lgkmcnt(10)
	v_mfma_f32_32x32x16_bf16 v[64:79], v[6:9], v[2:5], v[64:79]
	ds_read_b64 v[132:133], v238 offset:40960
	ds_read_b64 v[134:135], v239 offset:40960
	v_exp_f32_e32 v146, v146
	v_exp_f32_e32 v147, v147
	v_add_f32_e32 v0, v144, v0
	v_add_f32_e32 v0, v145, v0
	s_waitcnt lgkmcnt(10)
	v_mfma_f32_32x32x16_bf16 v[96:111], v[10:13], v[2:5], v[96:111]
	ds_read_b64 v[6:7], v240 offset:32768
	ds_read_b64 v[8:9], v241 offset:32768
	v_exp_f32_e32 v148, v148
	v_exp_f32_e32 v149, v149
	v_add_f32_e32 v0, v146, v0
	v_add_f32_e32 v0, v147, v0
	s_waitcnt lgkmcnt(10)
	v_mfma_f32_32x32x16_bf16 v[80:95], v[244:247], v[2:5], v[80:95]
	ds_read_b64 v[10:11], v242 offset:36864
	ds_read_b64 v[12:13], v243 offset:36864
	v_exp_f32_e32 v150, v150
	v_exp_f32_e32 v151, v151
	v_add_f32_e32 v0, v148, v0
	v_add_f32_e32 v0, v149, v0
	v_add_f32_e32 v0, v150, v0
	v_add_f32_e32 v0, v151, v0
	v_cvt_pk_bf16_f32 v2, v144, v145
	v_cvt_pk_bf16_f32 v3, v146, v147
	v_cvt_pk_bf16_f32 v4, v148, v149
	v_cvt_pk_bf16_f32 v5, v150, v151
	s_nop 1
	ds_read_b64 v[244:245], v242 offset:40960
	ds_read_b64 v[246:247], v243 offset:40960
	s_waitcnt lgkmcnt(12)
	v_mfma_f32_32x32x16_bf16 v[112:127], v[128:131], v[2:5], v[112:127]
	ds_read_b64 v[144:145], v242 offset:45056
	ds_read_b64 v[146:147], v243 offset:45056
	v_exp_f32_e32 v152, v152
	v_exp_f32_e32 v153, v153
	s_waitcnt lgkmcnt(12)
	v_mfma_f32_32x32x16_bf16 v[64:79], v[136:139], v[2:5], v[64:79]
	v_exp_f32_e32 v154, v154
	v_exp_f32_e32 v155, v155
	v_add_f32_e32 v0, v152, v0
	v_add_f32_e32 v0, v153, v0
	s_waitcnt lgkmcnt(10)
	v_mfma_f32_32x32x16_bf16 v[96:111], v[140:143], v[2:5], v[96:111]
	v_exp_f32_e32 v156, v156
	v_exp_f32_e32 v157, v157
	v_add_f32_e32 v0, v154, v0
	v_add_f32_e32 v0, v155, v0
	s_waitcnt lgkmcnt(8)
	v_mfma_f32_32x32x16_bf16 v[80:95], v[132:135], v[2:5], v[80:95]
	v_exp_f32_e32 v158, v158
	v_exp_f32_e32 v159, v159
	v_add_f32_e32 v0, v156, v0
	v_add_f32_e32 v0, v157, v0
	v_add_f32_e32 v0, v158, v0
	v_add_f32_e32 v0, v159, v0
	v_cvt_pk_bf16_f32 v2, v152, v153
	v_cvt_pk_bf16_f32 v3, v154, v155
	v_cvt_pk_bf16_f32 v4, v156, v157
	v_cvt_pk_bf16_f32 v5, v158, v159
	s_nop 1
	s_waitcnt lgkmcnt(6)
	v_mfma_f32_32x32x16_bf16 v[112:127], v[6:9], v[2:5], v[112:127]
	s_waitcnt lgkmcnt(4)
	v_mfma_f32_32x32x16_bf16 v[96:111], v[10:13], v[2:5], v[96:111]
	s_waitcnt lgkmcnt(2)
	v_mfma_f32_32x32x16_bf16 v[80:95], v[244:247], v[2:5], v[80:95]
	s_waitcnt lgkmcnt(0)
	v_mfma_f32_32x32x16_bf16 v[64:79], v[144:147], v[2:5], v[64:79]
	v_add_f32_e32 v227, v0, v227
	s_branch .LBB0_1386

.LBB0_1409:
	v_readfirstlane_b32 s38, v200
	ds_read_b128 v[2:5], v220 offset:24576
	ds_read_b128 v[6:9], v220 offset:28672
	ds_read_b128 v[10:13], v221 offset:24576
	ds_read_b128 v[244:247], v221 offset:28672
	s_add_i32 s16, s31, 2
	s_cmp_lt_u32 s31, s29
	s_cselect_b64 s[20:21], -1, 0
	s_cmp_ge_u32 s31, s29
	s_cselect_b64 s[18:19], -1, 0
	s_and_b64 vcc, exec, s[18:19]
	s_cbranch_vccnz .LBB0_1411
	s_mov_b32 s17, s83
	s_lshl_b64 s[4:5], s[16:17], 18
	s_add_u32 s4, s6, s4
	s_addc_u32 s5, s7, s5
	s_add_u32 s4, s4, s86
	s_addc_u32 s5, s5, s87
	s_mov_b32 m0, s38
	s_nop 0
	global_load_lds_dwordx4 v186, s[4:5]
	s_add_u32 m0, s38, 0x1000
	s_nop 0
	global_load_lds_dwordx4 v187, s[4:5]
.LBB0_1411:
	s_or_b32 s82, s31, 1
	s_lshl_b64 s[4:5], s[82:83], 7
	s_add_u32 s4, s8, s4
	s_addc_u32 s5, s9, s5
	s_add_u32 m0, s38, 0x8000
	s_nop 0
	global_load_lds_dwordx4 v196, s[4:5]
	s_add_u32 m0, s38, 0x9000
	s_nop 0
	global_load_lds_dwordx4 v197, s[4:5]
	s_add_u32 m0, s38, 0xa000
	s_nop 0
	global_load_lds_dwordx4 v198, s[4:5]
	s_add_u32 m0, s38, 0xb000
	s_nop 0
	global_load_lds_dwordx4 v199, s[4:5]
	v_cmp_lt_i32_e64 s[4:5], s31, v225
	s_and_saveexec_b64 s[22:23], s[4:5]
	s_cbranch_execz .LBB0_1413
	s_waitcnt lgkmcnt(3)
	v_mfma_f32_32x32x16_bf16 v[128:143], v[2:5], v[160:163], v[16:31]
	v_exp_f32_e32 v80, v80
	v_exp_f32_e32 v81, v81
	ds_read_b128 v[2:5], v222 offset:24576
	s_waitcnt lgkmcnt(3)
	v_mfma_f32_32x32x16_bf16 v[144:159], v[6:9], v[160:163], v[16:31]
	v_exp_f32_e32 v82, v82
	v_exp_f32_e32 v83, v83
	ds_read_b128 v[6:9], v222 offset:28672
	s_waitcnt lgkmcnt(3)
	v_mfma_f32_32x32x16_bf16 v[128:143], v[10:13], v[164:167], v[128:143]
	v_exp_f32_e32 v84, v84
	v_exp_f32_e32 v85, v85
	v_add_f32_e32 v0, 0, v80
	ds_read_b128 v[10:13], v223 offset:24576
	s_waitcnt lgkmcnt(3)
	v_mfma_f32_32x32x16_bf16 v[144:159], v[244:247], v[164:167], v[144:159]
	v_exp_f32_e32 v86, v86
	v_exp_f32_e32 v87, v87
	v_add_f32_e32 v0, v81, v0
	ds_read_b128 v[244:247], v223 offset:28672
	s_waitcnt lgkmcnt(3)
	v_mfma_f32_32x32x16_bf16 v[128:143], v[2:5], v[168:171], v[128:143]
	v_cvt_pk_bf16_f32 v208, v80, v81
	v_add_f32_e32 v0, v82, v0
	v_add_f32_e32 v0, v83, v0
	s_waitcnt lgkmcnt(2)
	v_mfma_f32_32x32x16_bf16 v[144:159], v[6:9], v[168:171], v[144:159]
	v_cvt_pk_bf16_f32 v209, v82, v83
	v_add_f32_e32 v0, v84, v0
	v_add_f32_e32 v0, v85, v0
	s_waitcnt lgkmcnt(1)
	v_mfma_f32_32x32x16_bf16 v[128:143], v[10:13], v[172:175], v[128:143]
	v_cvt_pk_bf16_f32 v210, v84, v85
	v_add_f32_e32 v0, v86, v0
	s_waitcnt lgkmcnt(0)
	v_mfma_f32_32x32x16_bf16 v[144:159], v[244:247], v[172:175], v[144:159]
	v_cvt_pk_bf16_f32 v211, v86, v87
	v_add_f32_e32 v0, v87, v0
	s_or_b64 exec, exec, s[22:23]
	v_cmp_le_i32_e32 vcc, s31, v225
	s_and_saveexec_b64 s[22:23], vcc
	ds_read_b64 v[6:7], v226 offset:8192
	ds_read_b64 v[8:9], v227 offset:8192
	ds_read_b64 v[10:11], v228 offset:20480
	ds_read_b64 v[12:13], v229 offset:20480
	ds_read_b64 v[242:243], v228 offset:12288
	ds_read_b64 v[244:245], v229 offset:12288
	ds_read_b64 v[80:81], v228 offset:16384
	ds_read_b64 v[82:83], v229 offset:16384
	ds_read_b64 v[84:85], v230 offset:8192
	ds_read_b64 v[86:87], v231 offset:8192
	s_waitcnt lgkmcnt(8)
	v_mfma_f32_32x32x16_bf16 v[64:79], v[6:9], v[208:211], v[64:79]
	ds_read_b64 v[6:7], v232 offset:20480
	ds_read_b64 v[8:9], v233 offset:20480
	v_exp_f32_e32 v88, v88
	v_exp_f32_e32 v89, v89
	s_waitcnt lgkmcnt(8)
	v_mfma_f32_32x32x16_bf16 v[112:127], v[10:13], v[208:211], v[112:127]
	ds_read_b64 v[10:11], v232 offset:12288
	ds_read_b64 v[12:13], v233 offset:12288
	v_exp_f32_e32 v90, v90
	v_exp_f32_e32 v91, v91
	v_add_f32_e32 v0, v88, v0
	v_add_f32_e32 v0, v89, v0
	s_waitcnt lgkmcnt(8)
	v_mfma_f32_32x32x16_bf16 v[48:63], v[242:245], v[208:211], v[48:63]
	ds_read_b64 v[242:243], v232 offset:16384
	ds_read_b64 v[244:245], v233 offset:16384
	v_exp_f32_e32 v92, v92
	v_exp_f32_e32 v93, v93
	v_add_f32_e32 v0, v90, v0
	v_add_f32_e32 v0, v91, v0
	s_waitcnt lgkmcnt(8)
	v_mfma_f32_32x32x16_bf16 v[32:47], v[80:83], v[208:211], v[32:47]
	ds_read_b64 v[80:81], v234 offset:8192
	ds_read_b64 v[82:83], v235 offset:8192
	v_exp_f32_e32 v94, v94
	v_exp_f32_e32 v95, v95
	v_add_f32_e32 v0, v92, v0
	v_add_f32_e32 v0, v93, v0
	v_add_f32_e32 v0, v94, v0
	v_add_f32_e32 v0, v95, v0
	v_cvt_pk_bf16_f32 v2, v88, v89
	v_cvt_pk_bf16_f32 v3, v90, v91
	v_cvt_pk_bf16_f32 v4, v92, v93
	v_cvt_pk_bf16_f32 v5, v94, v95
	s_nop 1
	ds_read_b64 v[88:89], v236 offset:20480
	ds_read_b64 v[90:91], v237 offset:20480
	s_waitcnt lgkmcnt(10)
	v_mfma_f32_32x32x16_bf16 v[64:79], v[84:87], v[2:5], v[64:79]
	ds_read_b64 v[92:93], v236 offset:12288
	ds_read_b64 v[94:95], v237 offset:12288
	v_exp_f32_e32 v96, v96
	v_exp_f32_e32 v97, v97
	s_waitcnt lgkmcnt(10)
	v_mfma_f32_32x32x16_bf16 v[112:127], v[6:9], v[2:5], v[112:127]
	ds_read_b64 v[84:85], v236 offset:16384
	ds_read_b64 v[86:87], v237 offset:16384
	v_exp_f32_e32 v98, v98
	v_exp_f32_e32 v99, v99
	v_add_f32_e32 v0, v96, v0
	v_add_f32_e32 v0, v97, v0
	s_waitcnt lgkmcnt(10)
	v_mfma_f32_32x32x16_bf16 v[48:63], v[10:13], v[2:5], v[48:63]
	ds_read_b64 v[6:7], v238 offset:8192
	ds_read_b64 v[8:9], v239 offset:8192
	v_exp_f32_e32 v100, v100
	v_exp_f32_e32 v101, v101
	v_add_f32_e32 v0, v98, v0
	v_add_f32_e32 v0, v99, v0
	s_waitcnt lgkmcnt(10)
	v_mfma_f32_32x32x16_bf16 v[32:47], v[242:245], v[2:5], v[32:47]
	ds_read_b64 v[10:11], v240 offset:12288
	ds_read_b64 v[12:13], v241 offset:12288
	v_exp_f32_e32 v102, v102
	v_exp_f32_e32 v103, v103
	v_add_f32_e32 v0, v100, v0
	v_add_f32_e32 v0, v101, v0
	v_add_f32_e32 v0, v102, v0
	v_add_f32_e32 v0, v103, v0
	v_cvt_pk_bf16_f32 v2, v96, v97
	v_cvt_pk_bf16_f32 v3, v98, v99
	v_cvt_pk_bf16_f32 v4, v100, v101
	v_cvt_pk_bf16_f32 v5, v102, v103
	s_nop 1
	ds_read_b64 v[242:243], v240 offset:16384
	ds_read_b64 v[244:245], v241 offset:16384
	s_waitcnt lgkmcnt(12)
	v_mfma_f32_32x32x16_bf16 v[64:79], v[80:83], v[2:5], v[64:79]
	ds_read_b64 v[96:97], v240 offset:20480
	ds_read_b64 v[98:99], v241 offset:20480
	v_exp_f32_e32 v104, v104
	v_exp_f32_e32 v105, v105
	s_waitcnt lgkmcnt(12)
	v_mfma_f32_32x32x16_bf16 v[112:127], v[88:91], v[2:5], v[112:127]
	v_exp_f32_e32 v106, v106
	v_exp_f32_e32 v107, v107
	v_add_f32_e32 v0, v104, v0
	v_add_f32_e32 v0, v105, v0
	s_waitcnt lgkmcnt(10)
	v_mfma_f32_32x32x16_bf16 v[48:63], v[92:95], v[2:5], v[48:63]
	v_exp_f32_e32 v108, v108
	v_exp_f32_e32 v109, v109
	v_add_f32_e32 v0, v106, v0
	v_add_f32_e32 v0, v107, v0
	s_waitcnt lgkmcnt(8)
	v_mfma_f32_32x32x16_bf16 v[32:47], v[84:87], v[2:5], v[32:47]
	v_exp_f32_e32 v110, v110
	v_exp_f32_e32 v111, v111
	v_add_f32_e32 v0, v108, v0
	v_add_f32_e32 v0, v109, v0
	v_add_f32_e32 v0, v110, v0
	v_add_f32_e32 v0, v111, v0
	v_cvt_pk_bf16_f32 v2, v104, v105
	v_cvt_pk_bf16_f32 v3, v106, v107
	v_cvt_pk_bf16_f32 v4, v108, v109
	v_cvt_pk_bf16_f32 v5, v110, v111
	s_nop 1
	s_waitcnt lgkmcnt(6)
	v_mfma_f32_32x32x16_bf16 v[64:79], v[6:9], v[2:5], v[64:79]
	s_waitcnt lgkmcnt(4)
	v_mfma_f32_32x32x16_bf16 v[48:63], v[10:13], v[2:5], v[48:63]
	s_waitcnt lgkmcnt(2)
	v_mfma_f32_32x32x16_bf16 v[32:47], v[242:245], v[2:5], v[32:47]
	s_waitcnt lgkmcnt(0)
	v_mfma_f32_32x32x16_bf16 v[112:127], v[96:99], v[2:5], v[112:127]
	v_add_f32_e32 v224, v224, v0
	s_branch .LBB0_1415

.LBB0_1420:
	ds_read_b128 v[2:5], v220
	ds_read_b128 v[6:9], v220 offset:4096
	ds_read_b128 v[10:13], v221
	ds_read_b128 v[244:247], v221 offset:4096
	s_add_i32 s82, s31, 3
	s_cmp_ge_u32 s82, s30
	s_cbranch_scc1 .LBB0_1424
	s_lshl_b64 s[22:23], s[82:83], 18
	s_add_u32 s22, s6, s22
	s_addc_u32 s23, s7, s23
	s_add_u32 s22, s22, s86
	s_addc_u32 s23, s23, s87
	s_add_u32 m0, s38, 0x6000
	s_nop 0
	global_load_lds_dwordx4 v186, s[22:23]
	s_add_u32 m0, s38, 0x7000
	s_nop 0
	global_load_lds_dwordx4 v187, s[22:23]
	s_andn2_b64 vcc, exec, s[20:21]
	s_cbranch_vccz .LBB0_1425

.LBB0_1423:
	s_waitcnt lgkmcnt(3)
	v_mfma_f32_32x32x16_bf16 v[80:95], v[2:5], v[160:163], v[16:31]
	v_exp_f32_e32 v128, v128
	v_exp_f32_e32 v129, v129
	ds_read_b128 v[2:5], v222
	s_waitcnt lgkmcnt(3)
	v_mfma_f32_32x32x16_bf16 v[96:111], v[6:9], v[160:163], v[16:31]
	v_exp_f32_e32 v130, v130
	v_exp_f32_e32 v131, v131
	ds_read_b128 v[6:9], v222 offset:4096
	s_waitcnt lgkmcnt(3)
	v_mfma_f32_32x32x16_bf16 v[80:95], v[10:13], v[164:167], v[80:95]
	v_exp_f32_e32 v132, v132
	v_exp_f32_e32 v133, v133
	v_add_f32_e32 v0, 0, v128
	ds_read_b128 v[10:13], v223
	s_waitcnt lgkmcnt(3)
	v_mfma_f32_32x32x16_bf16 v[96:111], v[244:247], v[164:167], v[96:111]
	v_exp_f32_e32 v134, v134
	v_exp_f32_e32 v135, v135
	v_add_f32_e32 v0, v129, v0
	ds_read_b128 v[244:247], v223 offset:4096
	s_waitcnt lgkmcnt(3)
	v_mfma_f32_32x32x16_bf16 v[80:95], v[2:5], v[168:171], v[80:95]
	v_cvt_pk_bf16_f32 v208, v128, v129
	v_add_f32_e32 v0, v130, v0
	v_add_f32_e32 v0, v131, v0
	s_waitcnt lgkmcnt(2)
	v_mfma_f32_32x32x16_bf16 v[96:111], v[6:9], v[168:171], v[96:111]
	v_cvt_pk_bf16_f32 v209, v130, v131
	v_add_f32_e32 v0, v132, v0
	v_add_f32_e32 v0, v133, v0
	s_waitcnt lgkmcnt(1)
	v_mfma_f32_32x32x16_bf16 v[80:95], v[10:13], v[172:175], v[80:95]
	v_cvt_pk_bf16_f32 v210, v132, v133
	v_add_f32_e32 v0, v134, v0
	s_waitcnt lgkmcnt(0)
	v_mfma_f32_32x32x16_bf16 v[96:111], v[244:247], v[172:175], v[96:111]
	v_cvt_pk_bf16_f32 v211, v134, v135
	v_add_f32_e32 v0, v135, v0
	s_or_b64 exec, exec, s[20:21]
	s_and_saveexec_b64 s[20:21], s[4:5]
	ds_read_b64 v[6:7], v226 offset:32768
	ds_read_b64 v[8:9], v227 offset:32768
	ds_read_b64 v[10:11], v228 offset:45056
	ds_read_b64 v[12:13], v229 offset:45056
	ds_read_b64 v[242:243], v228 offset:36864
	ds_read_b64 v[244:245], v229 offset:36864
	ds_read_b64 v[128:129], v228 offset:40960
	ds_read_b64 v[130:131], v229 offset:40960
	ds_read_b64 v[132:133], v230 offset:32768
	ds_read_b64 v[134:135], v231 offset:32768
	s_waitcnt lgkmcnt(8)
	v_mfma_f32_32x32x16_bf16 v[64:79], v[6:9], v[208:211], v[64:79]
	ds_read_b64 v[6:7], v232 offset:45056
	ds_read_b64 v[8:9], v233 offset:45056
	v_exp_f32_e32 v136, v136
	v_exp_f32_e32 v137, v137
	s_waitcnt lgkmcnt(8)
	v_mfma_f32_32x32x16_bf16 v[112:127], v[10:13], v[208:211], v[112:127]
	ds_read_b64 v[10:11], v232 offset:36864
	ds_read_b64 v[12:13], v233 offset:36864
	v_exp_f32_e32 v138, v138
	v_exp_f32_e32 v139, v139
	v_add_f32_e32 v0, v136, v0
	v_add_f32_e32 v0, v137, v0
	s_waitcnt lgkmcnt(8)
	v_mfma_f32_32x32x16_bf16 v[48:63], v[242:245], v[208:211], v[48:63]
	ds_read_b64 v[242:243], v232 offset:40960
	ds_read_b64 v[244:245], v233 offset:40960
	v_exp_f32_e32 v140, v140
	v_exp_f32_e32 v141, v141
	v_add_f32_e32 v0, v138, v0
	v_add_f32_e32 v0, v139, v0
	s_waitcnt lgkmcnt(8)
	v_mfma_f32_32x32x16_bf16 v[32:47], v[128:131], v[208:211], v[32:47]
	ds_read_b64 v[128:129], v234 offset:32768
	ds_read_b64 v[130:131], v235 offset:32768
	v_exp_f32_e32 v142, v142
	v_exp_f32_e32 v143, v143
	v_add_f32_e32 v0, v140, v0
	v_add_f32_e32 v0, v141, v0
	v_add_f32_e32 v0, v142, v0
	v_add_f32_e32 v0, v143, v0
	v_cvt_pk_bf16_f32 v2, v136, v137
	v_cvt_pk_bf16_f32 v3, v138, v139
	v_cvt_pk_bf16_f32 v4, v140, v141
	v_cvt_pk_bf16_f32 v5, v142, v143
	s_nop 1
	ds_read_b64 v[136:137], v236 offset:45056
	ds_read_b64 v[138:139], v237 offset:45056
	s_waitcnt lgkmcnt(10)
	v_mfma_f32_32x32x16_bf16 v[64:79], v[132:135], v[2:5], v[64:79]
	ds_read_b64 v[140:141], v236 offset:36864
	ds_read_b64 v[142:143], v237 offset:36864
	v_exp_f32_e32 v144, v144
	v_exp_f32_e32 v145, v145
	s_waitcnt lgkmcnt(10)
	v_mfma_f32_32x32x16_bf16 v[112:127], v[6:9], v[2:5], v[112:127]
	ds_read_b64 v[132:133], v236 offset:40960
	ds_read_b64 v[134:135], v237 offset:40960
	v_exp_f32_e32 v146, v146
	v_exp_f32_e32 v147, v147
	v_add_f32_e32 v0, v144, v0
	v_add_f32_e32 v0, v145, v0
	s_waitcnt lgkmcnt(10)
	v_mfma_f32_32x32x16_bf16 v[48:63], v[10:13], v[2:5], v[48:63]
	ds_read_b64 v[6:7], v238 offset:32768
	ds_read_b64 v[8:9], v239 offset:32768
	v_exp_f32_e32 v148, v148
	v_exp_f32_e32 v149, v149
	v_add_f32_e32 v0, v146, v0
	v_add_f32_e32 v0, v147, v0
	s_waitcnt lgkmcnt(10)
	v_mfma_f32_32x32x16_bf16 v[32:47], v[242:245], v[2:5], v[32:47]
	ds_read_b64 v[10:11], v240 offset:36864
	ds_read_b64 v[12:13], v241 offset:36864
	v_exp_f32_e32 v150, v150
	v_exp_f32_e32 v151, v151
	v_add_f32_e32 v0, v148, v0
	v_add_f32_e32 v0, v149, v0
	v_add_f32_e32 v0, v150, v0
	v_add_f32_e32 v0, v151, v0
	v_cvt_pk_bf16_f32 v2, v144, v145
	v_cvt_pk_bf16_f32 v3, v146, v147
	v_cvt_pk_bf16_f32 v4, v148, v149
	v_cvt_pk_bf16_f32 v5, v150, v151
	s_nop 1
	ds_read_b64 v[242:243], v240 offset:40960
	ds_read_b64 v[244:245], v241 offset:40960
	s_waitcnt lgkmcnt(12)
	v_mfma_f32_32x32x16_bf16 v[64:79], v[128:131], v[2:5], v[64:79]
	ds_read_b64 v[144:145], v240 offset:45056
	ds_read_b64 v[146:147], v241 offset:45056
	v_exp_f32_e32 v152, v152
	v_exp_f32_e32 v153, v153
	s_waitcnt lgkmcnt(12)
	v_mfma_f32_32x32x16_bf16 v[112:127], v[136:139], v[2:5], v[112:127]
	v_exp_f32_e32 v154, v154
	v_exp_f32_e32 v155, v155
	v_add_f32_e32 v0, v152, v0
	v_add_f32_e32 v0, v153, v0
	s_waitcnt lgkmcnt(10)
	v_mfma_f32_32x32x16_bf16 v[48:63], v[140:143], v[2:5], v[48:63]
	v_exp_f32_e32 v156, v156
	v_exp_f32_e32 v157, v157
	v_add_f32_e32 v0, v154, v0
	v_add_f32_e32 v0, v155, v0
	s_waitcnt lgkmcnt(8)
	v_mfma_f32_32x32x16_bf16 v[32:47], v[132:135], v[2:5], v[32:47]
	v_exp_f32_e32 v158, v158
	v_exp_f32_e32 v159, v159
	v_add_f32_e32 v0, v156, v0
	v_add_f32_e32 v0, v157, v0
	v_add_f32_e32 v0, v158, v0
	v_add_f32_e32 v0, v159, v0
	v_cvt_pk_bf16_f32 v2, v152, v153
	v_cvt_pk_bf16_f32 v3, v154, v155
	v_cvt_pk_bf16_f32 v4, v156, v157
	v_cvt_pk_bf16_f32 v5, v158, v159
	s_nop 1
	s_waitcnt lgkmcnt(6)
	v_mfma_f32_32x32x16_bf16 v[64:79], v[6:9], v[2:5], v[64:79]
	s_waitcnt lgkmcnt(4)
	v_mfma_f32_32x32x16_bf16 v[48:63], v[10:13], v[2:5], v[48:63]
	s_waitcnt lgkmcnt(2)
	v_mfma_f32_32x32x16_bf16 v[32:47], v[242:245], v[2:5], v[32:47]
	s_waitcnt lgkmcnt(0)
	v_mfma_f32_32x32x16_bf16 v[112:127], v[144:147], v[2:5], v[112:127]
	v_add_f32_e32 v224, v0, v224
	s_branch .LBB0_1428
